# v18 + half of the workgroups (bit 3 of block id) start each multi-tile GEMM phase ~4us late to desynchronize epilogues (power smoothing)
# speedup vs baseline: 1.0140x; 1.0041x over previous
; #define PH_PRO(x) do {} while (0)
; #define PH_GS(x) do {} while (0)
; #define PH_GT(x) do {} while (0)
; __global__ void __launch_bounds__(512, 2) fwd_megakernel(Args a) {
;     ...
;         if (kind == K_NONE) continue;
;         for (int rep = 0; rep <= ((DUP_MASK >> step) & 1); ++rep) {
;         if (rep) __syncthreads();
;         if (kind == K_PRO) { PH_PRO(prologue(a, lds, G, bid)); }
;         else if (kind == K_GSCALE) { pg8::StaticOrder S; S.init(gm.M, gm.N, G, bid); pg8::EpiScale E{obf, ldo, ss, bias, mode};
;             PH_GS((pg8::gemm_phase<pg8::EpiScale, pg8::StaticOrder, true, true>(lds, gm, S, E)));
;             if (cset) { const int rem = S.nwg % G;
;                 if (rem == 0 || bid >= rem) { int t_ = threadIdx.x; asm volatile("" : "+v"(t_)); const int nw = (rem == 0) ? G : G - rem;
;                     convert_set(a, lds, cset, __builtin_amdgcn_readfirstlane(t_ >> 6), t_ & 63, ((rem == 0) ? bid : bid - rem) * 8 + (t_ >> 6), nw * 8); } } }
;         else if (kind == K_GSCALET) { pg8::StaticOrder S; S.init(gm.M, gm.N, G, bid); pg8::EpiScaleT E{obf, ldo, ss};
;             PH_GT((pg8::gemm_phase<pg8::EpiScaleT, pg8::StaticOrder, true, true>(lds, gm, S, E))); }
;         else if (kind == K_GCONV) { pg8::StaticOrder S; S.init(gm.M, gm.N, G, bid); pg8::EpiConv E{(bf16*)(ws + WS_HM), ss, a.in[10] + (size_t)layer * 3 * FF2, a.in[11] + (size_t)layer * FF2};
;             pg8::gemm_phase<pg8::EpiConv, pg8::StaticOrder, true, true>(lds, gm, S, E);
.LBB0_8:
	s_lshl_b32 s98, 1, s36
	s_and_b32 s98, s98, 0x1246
	s_cbranch_scc0 .Lmy_nostag
	v_readlane_b32 s98, v250, 0
	s_nop 3
	s_bitcmp1_b32 s98, 3
	s_cbranch_scc0 .Lmy_nostag
	s_sleep 127
